# prep items: dead head-vector iterations skipped, V-transpose tile loads issued 4 at a time
# baseline (speedup 1.0000x reference)
; DI int TID() { int t = threadIdx.x; asm volatile("" : "+v"(t)); return t; }
; DI void prep_item(const Params& p, int L, int item, char* smem) {
;   const int tid = TID();
;   const int b = item >> 5, s0 = (item & 31) * 64;
;   const size_t t0 = (size_t)b * S + s0;
;   const int sub = tid & 7;
; #pragma unroll 1
;   for (int jb = 0; jb < 44; jb += 4) {
;     u32x2 v0[4], v1[4];
; #pragma unroll
;     for (int u = 0; u < 4; ++u) {
;       const int job = (tid >> 3) + 32 * (jb + u);
;       const int tok = job & 63, vec = job >> 6;
;       int col;
;       if (vec < 4) col = 64 * vec; else if (vec < 8) col = 256 + 64 * (vec - 4); else if (vec < 12) col = 1964 + 64 * (vec - 8);
;       else if (vec < 16) col = 2220 + 64 * (vec - 12); else if (vec < 20) col = 1312 + 64 * (vec - 16); else if (vec == 20) col = 1696; else col = 1824;
;       const bfu* src = p.proj + (t0 + tok) * PJ + col + sub * 8;
;       v0[u] = *(const u32x2*)src; v1[u] = *(const u32x2*)(src + 4);
;     }
; #pragma unroll
;     for (int u = 0; u < 4; ++u) {
;       const int job = (tid >> 3) + 32 * (jb + u);
;       const int tok = job & 63, vec = job >> 6;
;       if ((vec < 8) ? (FUSE_MASK & 1) : (FUSE_MASK & 2)) continue;
.LBB0_520:
	s_andn2_b64 vcc, exec, s[2:3]
	s_cbranch_vccnz .LBB0_751
	s_sub_i32 s2, s89, 24
	v_mov_b32_e32 v17, v224
	s_lshr_b32 s96, s2, 5
	s_lshl_b32 s2, s2, 6
	s_and_b32 s12, s2, 0x7c0
	s_lshl_b64 s[4:5], s[96:97], 11
	v_ashrrev_i32_e32 v29, 3, v17
	s_or_b32 s4, s4, s12
	v_and_b32_e32 v6, 63, v29
	v_bitop3_b32 v7, v29, 32, 63 bitop3:0x6c
	v_lshlrev_b32_e32 v27, 3, v17
	v_or_b32_e32 v0, s4, v6
	v_mov_b32_e32 v1, s5
	v_or_b32_e32 v2, s4, v7
	v_mov_b32_e32 v3, s5
	v_mov_b64_e32 v[4:5], s[68:69]
	v_and_b32_e32 v16, 56, v27
	v_lshlrev_b64 v[18:19], 7, v[0:1]
	v_lshlrev_b64 v[20:21], 7, v[2:3]
	v_mad_u64_u32 v[0:1], s[2:3], v0, s1, v[4:5]
	v_mov_b32_e32 v3, 0x1580
	v_mad_u32_u24 v1, s5, v3, v1
	v_lshlrev_b32_e32 v188, 1, v16
	v_lshl_add_u64 v[22:23], v[0:1], 0, v[188:189]
	v_mad_u64_u32 v[0:1], s[2:3], v2, s1, v[4:5]
	v_writelane_b32 v255, s11, 38
	s_mov_b32 s11, s35
	s_lshl_b32 s35, s96, 2
	v_mad_u32_u24 v1, s5, v3, v1
	s_mov_b64 s[92:93], s[84:85]
	s_add_i32 s94, s35, -16
	s_add_i32 s95, s35, -12
	s_add_i32 s15, s35, -8
	v_lshl_add_u64 v[24:25], v[0:1], 0, v[188:189]
	v_or_b32_e32 v26, s12, v6
	v_or_b32_e32 v28, s12, v7
	s_mov_b32 s14, 12
	v_add_u32_e32 v29, 0x200, v29
	s_branch .LBB0_524

; DI int TID() { int t = threadIdx.x; asm volatile("" : "+v"(t)); return t; }
; DI void tr_load(const bfu* __restrict__ src, int pitch, bfu* T) {
;   const int tid = TID();
; #pragma unroll
;   for (int j = 0; j < 4; ++j) {
;     int c = tid + 256 * j; int tok = c >> 4, q = c & 15;
;     u32x2 v = *(const u32x2*)(src + (size_t)tok * pitch + q * 4);
;     *(unsigned*)(T + tok * TP + q * 4) = v[0];
;     *(unsigned*)(T + tok * TP + q * 4 + 2) = v[1];
;   }
; }
; DI void prep_item(const Params& p, int L, int item, char* smem) {
;     ...
;   for (int grp = 0; grp < 2; ++grp) {
;     __syncthreads();
; #pragma unroll 1
;     for (int q = 0; q < 5; ++q) {
;       int v = grp * 5 + q; int col;
;       if (v < 4) col = 512 + 64 * v; else if (v < 8) col = 2476 + 64 * (v - 4); else if (v == 8) col = 1760; else col = 1888;
;       tr_load(p.proj + t0 * PJ + col, PJ, T + q * 64 * TP);
;     }
.LBB0_734:
	s_lshl_b64 s[6:7], s[96:97], 1
	v_mov_b32_e32 v4, v224
	s_add_u32 s6, s15, s6
	s_addc_u32 s7, s22, s7
	v_lshlrev_b32_e32 v0, 3, v4
	v_and_b32_e32 v188, 0x78, v0
	v_lshl_add_u64 v[0:1], s[6:7], 0, v[188:189]
	v_ashrrev_i32_e32 v60, 4, v4
	v_mad_i64_i32 v[64:65], s[6:7], v60, s1, v[0:1]
	global_load_dwordx2 v[72:73], v[64:65], off
	v_add_u32_e32 v61, 0x100, v4
	v_ashrrev_i32_e32 v61, 4, v61
	v_mad_i64_i32 v[66:67], s[6:7], v61, s1, v[0:1]
	global_load_dwordx2 v[74:75], v[66:67], off
	v_add_u32_e32 v62, 0x200, v4
	v_ashrrev_i32_e32 v62, 4, v62
	v_mad_i64_i32 v[68:69], s[6:7], v62, s1, v[0:1]
	global_load_dwordx2 v[76:77], v[68:69], off
	v_add_u32_e32 v63, 0x300, v4
	v_ashrrev_i32_e32 v63, 4, v63
	v_mad_i64_i32 v[70:71], s[6:7], v63, s1, v[0:1]
	global_load_dwordx2 v[78:79], v[70:71], off
	v_mul_lo_u32 v60, v60, s13
	v_add3_u32 v60, v60, v188, s29
	v_mul_lo_u32 v61, v61, s13
	v_add3_u32 v61, v61, v188, s29
	v_mul_lo_u32 v62, v62, s13
	v_add3_u32 v62, v62, v188, s29
	v_mul_lo_u32 v63, v63, s13
	v_add3_u32 v63, v63, v188, s29
	s_add_i32 s31, s31, 1
	s_add_i32 s8, s8, 64
	s_add_i32 s9, s9, 1
	s_waitcnt vmcnt(3)
	ds_write2_b32 v60, v72, v73 offset1:1
	s_waitcnt vmcnt(2)
	ds_write2_b32 v61, v74, v75 offset1:1
	s_waitcnt vmcnt(1)
	ds_write2_b32 v62, v76, v77 offset1:1
	s_waitcnt vmcnt(0)
	ds_write2_b32 v63, v78, v79 offset1:1
	s_addk_i32 s29, 0x2100
	s_cmpk_eq_u32 s29, 0xa500
	s_cbranch_scc1 .LBB0_741
